# S5 scan loop: per-chunk rstd LDS reads prefetched one chunk ahead (no LDS wait on the scan chain)
# baseline (speedup 1.0000x reference)
; __device__ __forceinline__ unsigned pk2(float lo, float hi) { f32x2 v = {lo, hi}; bf16x2_t b = __builtin_convertvector(v, bf16x2_t); return __builtin_bit_cast(unsigned, b); }
; __device__ __forceinline__ void s5_disc(float lr, float li, float step, float& lbr, float& lbi, float& fr, float& fi) {
;     const float mag = expf(lr * step); float sn, cs; sincos_2pi(li * step * 0.15915494309189535f, sn, cs);
;     lbr = mag * cs; lbi = mag * sn;
;     const float den = lr * lr + li * li;
;     fr = ((lbr - 1.0f) * lr + lbi * li) / den; fi = (lbi * lr - (lbr - 1.0f) * li) / den;
; }
; __device__ __forceinline__ void s5_phase(const bf16_t* __restrict__ HN, bf16_t* __restrict__ Y, const float* __restrict__ rsq, const float* __restrict__ gmix, const float* lam_re, const float* lam_im, const float* log_step, ...
;     ...
;         if (hw < 2) {
;             const int p = 32 * hw + r32;
;             const float step = expf(log_step[g]);
;             float lbr, lbi, fr, fi; s5_disc(lam_re[g * SSM_P + p], lam_im[g * SSM_P + p], step, lbr, lbi, fr, fi);
;             bf16x8 bbr, bbi;
;             { const float* br = b_re + (size_t)(g * SSM_P + p) * SSM_H + hi * 8; const float* bi = b_im + (size_t)(g * SSM_P + p) * SSM_H + hi * 8;
;               float vr[8], vi[8];
; #pragma unroll
;               for (int j = 0; j < 8; ++j) { vr[j] = fr * br[j] - fi * bi[j]; vi[j] = fr * bi[j] + fi * br[j]; }
;               u32x4 w; w.x = pk2(vr[0], vr[1]); w.y = pk2(vr[2], vr[3]); w.z = pk2(vr[4], vr[5]); w.w = pk2(vr[6], vr[7]); bbr = __builtin_bit_cast(bf16x8, w);
;               w.x = pk2(vi[0], vi[1]); w.y = pk2(vi[2], vi[3]); w.z = pk2(vi[4], vi[5]); w.w = pk2(vi[6], vi[7]); bbi = __builtin_bit_cast(bf16x8, w); }
;             float gA[8];
; #pragma unroll
;             for (int j = 0; j < 8; ++j) gA[j] = gmix[g * SSM_H + hi * 8 + j];
;             const float l2r = lbr * lbr - lbi * lbi, l2i = 2.0f * lbr * lbi, l3r = l2r * lbr - l2i * lbi, l3i = l2r * lbi + l2i * lbr, l4r = l2r * l2r - l2i * l2i, l4i = 2.0f * l2r * l2i;
;             float xr = 0.f, xi = 0.f;
;             u32x4 ua[2];
; #pragma unroll
;             for (int mb = 0; mb < 2; ++mb) ua[mb] = *(const u32x4*)(ubase + (size_t)(mb * 32 + r32) * DM + hi * 8);
.LBB0_182:
	s_or_b64 exec, exec, s[16:17]
	v_lshlrev_b64 v[0:1], 6, v[0:1]
	v_lshl_add_u64 v[16:17], v[70:71], 0, v[0:1]
	global_load_dwordx4 v[8:11], v[16:17], off
	v_lshl_add_u64 v[0:1], v[68:69], 0, v[0:1]
	global_load_dwordx4 v[12:15], v[0:1], off
	s_nop 0
	global_load_dwordx4 v[16:19], v[16:17], off offset:16
	s_nop 0
	global_load_dwordx4 v[20:23], v[0:1], off offset:16
	v_mul_f32_e32 v25, v5, v2
	v_or_b32_e32 v0, s68, v66
	v_lshlrev_b32_e32 v96, 1, v66
	v_mul_f32_e32 v26, 0x3fb8aa3b, v25
	s_mov_b32 s2, 0x3fb8aa3b
	v_mov_b32_e32 v111, v97
	v_ashrrev_i32_e32 v1, 31, v0
	v_lshl_add_u64 v[2:3], s[6:7], 0, v[96:97]
	v_fma_f32 v28, v25, s2, -v26
	v_rndne_f32_e32 v30, v26
	v_lshl_add_u64 v[0:1], v[0:1], 2, s[8:9]
	v_lshl_add_u64 v[2:3], v[2:3], 0, v[110:111]
	v_fmac_f32_e32 v28, 0x32a5705f, v25
	v_sub_f32_e32 v26, v26, v30
	s_mov_b32 s2, 0x20000
	v_cvt_i32_f32_e32 v40, v30
	global_load_dwordx4 v[32:35], v[0:1], off offset:16
	global_load_dwordx4 v[36:39], v[0:1], off
	v_add_f32_e32 v0, v26, v28
	v_add_co_u32_e32 v30, vcc, s2, v2
	v_exp_f32_e32 v26, v0
	s_nop 0
	v_addc_co_u32_e32 v31, vcc, 0, v3, vcc
	global_load_dwordx4 v[0:3], v[2:3], off
	s_nop 0
	global_load_dwordx4 v[56:59], v[30:31], off
	s_mov_b32 s2, 0xc2ce8ed0
	v_ldexp_f32 v26, v26, v40
	v_cmp_ngt_f32_e32 vcc, s2, v25
	s_mov_b32 s2, 0x42b17218
	v_mov_b32_e32 v24, v5
	v_cndmask_b32_e32 v26, 0, v26, vcc
	v_cmp_nlt_f32_e32 vcc, s2, v25
	v_mov_b32_e32 v27, v5
	v_mov_b32_e32 v29, v4
	v_cndmask_b32_e32 v25, v242, v26, vcc
	v_mul_f32_e32 v114, v25, v6
	v_fma_f32 v115, v25, v7, -1.0
	v_mul_f32_e32 v112, v25, v7
	v_pk_mul_f32 v[6:7], v[4:5], v[114:115]
	v_mov_b32_e32 v26, v114
	v_mov_b32_e32 v28, v115
	v_add_f32_e32 v25, v6, v7
	v_pk_mul_f32 v[6:7], v[24:25], v[26:27] op_sel_hi:[0,1]
	v_pk_mul_f32 v[4:5], v[4:5], v[28:29] op_sel_hi:[0,1]
	v_add_f32_e32 v5, v7, v5
	v_sub_f32_e32 v6, v6, v4
	v_div_scale_f32 v4, s[2:3], v5, v5, v25
	v_div_scale_f32 v24, s[2:3], v5, v5, v6
	v_rcp_f32_e32 v26, v4
	v_rcp_f32_e32 v27, v24
	v_div_scale_f32 v7, vcc, v25, v5, v25
	v_fma_f32 v29, -v4, v26, 1.0
	v_fma_f32 v30, -v24, v27, 1.0
	v_fmac_f32_e32 v26, v29, v26
	v_div_scale_f32 v28, s[6:7], v6, v5, v6
	v_fmac_f32_e32 v27, v30, v27
	v_mul_f32_e32 v29, v7, v26
	v_mul_f32_e32 v30, v28, v27
	v_fma_f32 v31, -v4, v29, v7
	v_fma_f32 v40, -v24, v30, v28
	v_fmac_f32_e32 v29, v31, v26
	v_fmac_f32_e32 v30, v40, v27
	v_fma_f32 v4, -v4, v29, v7
	v_fma_f32 v7, -v24, v30, v28
	v_div_fmas_f32 v4, v4, v26, v29
	s_mov_b64 vcc, s[6:7]
	v_div_fmas_f32 v7, v7, v27, v30
	v_div_fixup_f32 v4, v4, v5, v25
	v_div_fixup_f32 v6, v7, v5, v6
	s_add_u32 s6, s34, s66
	v_mov_b32_e32 v136, 0
	v_xor_b32_e32 v128, 0x80000000, v114
	v_mov_b32_e32 v129, v114
	s_waitcnt vmcnt(7)
	v_pk_mul_f32 v[24:25], v[8:9], v[6:7] op_sel_hi:[1,0]
	v_pk_mul_f32 v[8:9], v[8:9], v[4:5] op_sel_hi:[1,0]
	v_pk_mul_f32 v[26:27], v[6:7], v[10:11] op_sel_hi:[0,1]
	v_pk_mul_f32 v[10:11], v[4:5], v[10:11] op_sel_hi:[0,1]
	s_waitcnt vmcnt(6)
	v_pk_fma_f32 v[24:25], v[12:13], v[4:5], v[24:25] op_sel_hi:[1,0,1] neg_lo:[0,0,1] neg_hi:[0,0,1]
	v_pk_fma_f32 v[8:9], v[12:13], v[6:7], v[8:9] op_sel_hi:[1,0,1]
	v_pk_fma_f32 v[12:13], v[4:5], v[14:15], v[26:27] op_sel_hi:[0,1,1] neg_lo:[0,0,1] neg_hi:[0,0,1]
	v_pk_fma_f32 v[10:11], v[6:7], v[14:15], v[10:11] op_sel_hi:[0,1,1]
	s_waitcnt vmcnt(5)
	v_pk_mul_f32 v[14:15], v[6:7], v[16:17] op_sel_hi:[0,1]
	v_pk_mul_f32 v[16:17], v[4:5], v[16:17] op_sel_hi:[0,1]
	s_waitcnt vmcnt(4)
	v_pk_fma_f32 v[14:15], v[4:5], v[20:21], v[14:15] op_sel_hi:[0,1,1] neg_lo:[0,0,1] neg_hi:[0,0,1]
	v_pk_fma_f32 v[16:17], v[6:7], v[20:21], v[16:17] op_sel_hi:[0,1,1]
	v_pk_mul_f32 v[20:21], v[6:7], v[18:19] op_sel_hi:[0,1]
	v_pk_fma_f32 v[20:21], v[4:5], v[22:23], v[20:21] op_sel_hi:[0,1,1] neg_lo:[0,0,1] neg_hi:[0,0,1]
	v_pk_mul_f32 v[4:5], v[4:5], v[18:19] op_sel_hi:[0,1]
	v_pk_fma_f32 v[4:5], v[6:7], v[22:23], v[4:5] op_sel_hi:[0,1,1]
	v_cvt_pk_bf16_f32 v47, v4, v5
	v_mul_f32_e32 v4, v114, v114
	v_fma_f32 v116, v112, v112, -v4
	v_add_f32_e32 v4, v112, v112
	v_mul_f32_e32 v119, v114, v4
	v_add_f32_e32 v6, v116, v116
	v_mul_f32_e32 v4, v114, v119
	v_mul_f32_e32 v121, v112, v119
	v_mul_f32_e32 v5, v119, v119
	v_mul_f32_e32 v126, v119, v6
	v_fmac_f32_e32 v121, v114, v116
	v_fma_f32 v122, v112, v116, -v4
	v_fma_f32 v124, v116, v116, -v5
	v_xor_b32_e32 v127, 0x80000000, v126
	s_addc_u32 s7, s35, s67
	v_cvt_pk_bf16_f32 v40, v24, v25
	v_cvt_pk_bf16_f32 v41, v12, v13
	v_cvt_pk_bf16_f32 v42, v14, v15
	v_cvt_pk_bf16_f32 v43, v20, v21
	v_cvt_pk_bf16_f32 v44, v8, v9
	v_cvt_pk_bf16_f32 v45, v10, v11
	v_cvt_pk_bf16_f32 v46, v16, v17
	s_mov_b32 s2, 0
	v_xor_b32_e32 v118, 0x80000000, v119
	v_xor_b32_e32 v120, 0x80000000, v121
	v_mov_b32_e32 v113, v112
	v_mov_b32_e32 v125, v124
	v_pk_mov_b32 v[130:131], v[128:129], v[128:129] op_sel:[1,0]
	v_mov_b32_e32 v117, v116
	v_mov_b32_e32 v123, v122
	v_mov_b32_e32 v115, v128
	v_mov_b32_e32 v132, v127
	v_mov_b32_e32 v133, v126
	v_lshl_add_u64 v[134:135], v[106:107], 0, s[6:7]
	s_mov_b64 s[6:7], 0
	v_mov_b32_e32 v96, v168
	v_mov_b32_e32 v137, v136
	v_add_u32_e32 v252, 0xffffff80, v96
	ds_read_b32 v253, v96
	ds_read_b32 v252, v252
	s_waitcnt lgkmcnt(0)
	s_branch .LBB0_184
; #define LAS __attribute__((address_space(3)))
; __device__ __forceinline__ void s5_phase(const bf16_t* __restrict__ HN, bf16_t* __restrict__ Y, const float* __restrict__ rsq, const float* __restrict__ gmix, const float* lam_re, const float* lam_im, const float* log_step, ...
;     ...
;             for (int c = 0; c <= NC; ++c) {
;                 if (c < NC) {
;                     LAS unsigned char* xs = XS + (c & 1) * S5_XS_BUF + p * 4;
;                     u32x4 un[2] = {ua[0], ua[1]};
;                     if (c + 1 < NC) {
; #pragma unroll
;                         for (int mb = 0; mb < 2; ++mb) un[mb] = *(const u32x4*)(ubase + (size_t)((c + 1) * 64 + mb * 32 + r32) * DM + hi * 8); }
; #pragma unroll
;                     for (int mb = 0; mb < 2; ++mb) {
;                         const float rs = RT[c * 64 + mb * 32 + r32]; u32x4 o;
; #pragma unroll
;                         for (int q = 0; q < 4; ++q) o[q] = pk2(bflo(ua[mb][q]) * rs * gA[2 * q], bfhi(ua[mb][q]) * rs * gA[2 * q + 1]);
;                         f32x16 zr, zi;
; #pragma unroll
;                         for (int r = 0; r < 16; ++r) { zr[r] = 0.f; zi[r] = 0.f; }
;                         zr = __builtin_amdgcn_mfma_f32_32x32x16_bf16(__builtin_bit_cast(bf16x8, o), bbr, zr, 0, 0, 0);
;                         zi = __builtin_amdgcn_mfma_f32_32x32x16_bf16(__builtin_bit_cast(bf16x8, o), bbi, zi, 0, 0, 0);
; #pragma unroll
;                         for (int grp = 0; grp < 8; ++grp) {
;                             const int r0 = 4 * (grp >> 1);
;                             float c1r, c1i, fr_, fi_, er, ei;
;                             cfma(c1r, c1i, lbr, lbi, zr[r0], zi[r0], zr[r0 + 1], zi[r0 + 1]);
;                             cfma(fr_, fi_, lbr, lbi, c1r, c1i, zr[r0 + 2], zi[r0 + 2]);
;                             cfma(er, ei, lbr, lbi, fr_, fi_, zr[r0 + 3], zi[r0 + 3]);
;                             const float Xr = other_half(xr), Xi = other_half(xi);
;                             float ar, ai, br_, bi_, cr, ci;
;                             cfma(ar, ai, lbr, lbi, Xr, Xi, zr[r0], zi[r0]);
;                             cfma(br_, bi_, l2r, l2i, Xr, Xi, c1r, c1i);
;                             cfma(cr, ci, l3r, l3i, Xr, Xi, fr_, fi_);
;                             cfma(xr, xi, l4r, l4i, Xr, Xi, er, ei);
;                             const bool act = (hi == (grp & 1));
.LBB0_183:
	v_mov_b32_e32 v4, v252
	v_add_u32_e32 v250, 0x80, v96
	ds_read_b32 v252, v250
	v_lshlrev_b32_e32 v6, 16, v0
	v_and_b32_e32 v7, 0xffff0000, v0
	v_lshlrev_b32_e32 v0, 16, v1
	v_and_b32_e32 v1, 0xffff0000, v1
	v_pk_mul_f32 v[0:1], v[4:5], v[0:1] op_sel_hi:[0,1]
	v_pk_mul_f32 v[0:1], v[38:39], v[0:1]
	v_pk_mul_f32 v[6:7], v[4:5], v[6:7] op_sel_hi:[0,1]
	v_cvt_pk_bf16_f32 v17, v0, v1
	v_lshlrev_b32_e32 v0, 16, v2
	v_and_b32_e32 v1, 0xffff0000, v2
	v_pk_mul_f32 v[0:1], v[4:5], v[0:1] op_sel_hi:[0,1]
	v_pk_mul_f32 v[0:1], v[32:33], v[0:1]
	v_pk_mul_f32 v[6:7], v[36:37], v[6:7]
	v_cvt_pk_bf16_f32 v18, v0, v1
	v_lshlrev_b32_e32 v0, 16, v3
	v_and_b32_e32 v1, 0xffff0000, v3
	v_pk_mul_f32 v[0:1], v[4:5], v[0:1] op_sel_hi:[0,1]
	v_pk_mul_f32 v[0:1], v[34:35], v[0:1]
	v_cvt_pk_bf16_f32 v16, v6, v7
	v_cvt_pk_bf16_f32 v19, v0, v1
	v_mov_b32_e32 v196, v137
	v_mov_b32_e32 v197, v137
	v_mfma_f32_32x32x16_bf16 v[0:15], v[16:19], v[40:43], 0
	v_mov_b32_e32 v198, v136
	v_mov_b32_e32 v199, v136
	v_permlane32_swap_b32_e32 v196, v197
	s_nop 0
	v_permlane32_swap_b32_e32 v198, v199
	v_xor_b32_e32 v196, v197, v196
	v_mfma_f32_32x32x16_bf16 v[16:31], v[16:19], v[44:47], 0
	v_xor_b32_e32 v197, v199, v198
	v_xor_b32_e32 v136, v197, v136
	s_nop 2
	v_mov_b32_e32 v201, v0
	v_xor_b32_e32 v137, v196, v137
	v_mov_b32_e32 v196, v0
	s_bitcmp1_b32 s2, 0
	s_cselect_b32 s3, 0x4510, 0
	s_nop 1
	v_mov_b32_e32 v197, v16
	v_mov_b32_e32 v200, v16
	v_mov_b32_e32 v16, v1
	v_pk_fma_f32 v[0:1], v[128:129], v[200:201], v[16:17]
	v_pk_fma_f32 v[198:199], v[128:129], v[136:137], v[196:197]
	v_pk_fma_f32 v[0:1], v[112:113], v[196:197], v[0:1]
	v_mov_b32_e32 v196, v18
	v_mov_b32_e32 v197, v2
	v_pk_fma_f32 v[196:197], v[114:115], v[0:1], v[196:197]
	v_mov_b32_e32 v2, v19
	v_pk_fma_f32 v[196:197], v[112:113], v[0:1], v[196:197] op_sel:[0,0,1] op_sel_hi:[1,1,0]
	v_add_u32_e32 v109, s3, v139
	v_pk_fma_f32 v[2:3], v[114:115], v[196:197], v[2:3]
	v_pk_fma_f32 v[198:199], v[112:113], v[136:137], v[198:199] op_sel:[0,0,1] op_sel_hi:[1,1,0]
	v_pk_fma_f32 v[2:3], v[112:113], v[196:197], v[2:3] op_sel:[0,0,1] op_sel_hi:[1,1,0]
	v_pk_fma_f32 v[16:17], v[118:119], v[136:137], v[0:1]
	v_pk_fma_f32 v[210:211], v[120:121], v[136:137], v[196:197]
	v_pk_fma_f32 v[18:19], v[132:133], v[136:137], v[2:3]
	v_add_u32_e32 v202, v109, v143
	v_pk_fma_f32 v[16:17], v[116:117], v[136:137], v[16:17] op_sel:[0,1,0] op_sel_hi:[1,0,1]
	v_pk_fma_f32 v[210:211], v[122:123], v[136:137], v[210:211] op_sel:[0,1,0] op_sel_hi:[1,0,1]
	v_pk_fma_f32 v[18:19], v[124:125], v[136:137], v[18:19] op_sel:[0,1,0] op_sel_hi:[1,0,1]
	v_pk_mov_b32 v[136:137], v[198:199], v[198:199] op_sel:[1,0]
	v_add_u32_e32 v203, v202, v142
	v_cvt_pk_bf16_f32 v136, v136, v137
	v_cvt_pk_bf16_f32 v16, v16, v17
	v_add_u32_e32 v212, v202, v144
	ds_write_b32 v202, v136
	ds_write_b32 v203, v16
	v_cvt_pk_bf16_f32 v16, v210, v211
	v_add_u32_e32 v213, v202, v145
	ds_write_b32 v212, v16
	v_cvt_pk_bf16_f32 v16, v18, v19
	ds_write_b32 v213, v16
	v_mov_b32_e32 v16, v18
	v_mov_b32_e32 v17, v18
	v_mov_b32_e32 v136, v19
	v_mov_b32_e32 v137, v19
	v_permlane32_swap_b32_e32 v16, v17
	s_nop 0
	v_permlane32_swap_b32_e32 v136, v137
	v_xor_b32_e32 v136, v136, v137
	v_xor_b32_e32 v16, v16, v17
	v_xor_b32_e32 v17, v136, v19
	v_xor_b32_e32 v16, v16, v18
	v_pk_fma_f32 v[18:19], v[114:115], v[16:17], v[200:201]
	v_pk_fma_f32 v[0:1], v[118:119], v[16:17], v[0:1] op_sel:[0,1,0] op_sel_hi:[1,0,1]
	v_add_u32_e32 v214, v109, v147
	v_pk_fma_f32 v[18:19], v[112:113], v[16:17], v[18:19] op_sel:[0,0,1] op_sel_hi:[1,1,0]
	v_pk_fma_f32 v[0:1], v[116:117], v[16:17], v[0:1]
	v_pk_fma_f32 v[136:137], v[120:121], v[16:17], v[196:197] op_sel:[0,1,0] op_sel_hi:[1,0,1]
	v_pk_fma_f32 v[2:3], v[132:133], v[16:17], v[2:3] op_sel:[0,1,0] op_sel_hi:[1,0,1]
	v_add_u32_e32 v215, v214, v146
	v_pk_fma_f32 v[136:137], v[122:123], v[16:17], v[136:137]
	v_pk_fma_f32 v[2:3], v[124:125], v[16:17], v[2:3]
	v_cvt_pk_bf16_f32 v16, v18, v19
	v_cvt_pk_bf16_f32 v0, v0, v1
	v_add_u32_e32 v216, v214, v148
	ds_write_b32 v214, v16
	ds_write_b32 v215, v0
	v_cvt_pk_bf16_f32 v0, v136, v137
	v_add_u32_e32 v217, v214, v149
	ds_write_b32 v216, v0
	v_cvt_pk_bf16_f32 v0, v2, v3
	ds_write_b32 v217, v0
	v_mov_b32_e32 v0, v2
	v_mov_b32_e32 v1, v2
	v_mov_b32_e32 v16, v3
	v_mov_b32_e32 v17, v3
	v_permlane32_swap_b32_e32 v0, v1
	s_nop 0
	v_permlane32_swap_b32_e32 v16, v17
	v_xor_b32_e32 v16, v16, v17
	v_xor_b32_e32 v0, v0, v1
	v_xor_b32_e32 v1, v16, v3
	v_xor_b32_e32 v0, v0, v2
	v_mov_b32_e32 v2, v20
	v_mov_b32_e32 v3, v4
	v_mov_b32_e32 v18, v5
	v_mov_b32_e32 v19, v21
	v_pk_fma_f32 v[18:19], v[128:129], v[2:3], v[18:19]
	v_mov_b32_e32 v5, v20
	v_pk_fma_f32 v[4:5], v[112:113], v[4:5], v[18:19]
	v_mov_b32_e32 v20, v22
	v_mov_b32_e32 v21, v6
	v_pk_fma_f32 v[20:21], v[114:115], v[4:5], v[20:21]
	v_pk_fma_f32 v[16:17], v[114:115], v[0:1], v[2:3]
	v_pk_fma_f32 v[20:21], v[112:113], v[4:5], v[20:21] op_sel:[0,0,1] op_sel_hi:[1,1,0]
	v_mov_b32_e32 v6, v23
	v_pk_fma_f32 v[16:17], v[112:113], v[0:1], v[16:17] op_sel:[0,0,1] op_sel_hi:[1,1,0]
	v_pk_fma_f32 v[18:19], v[118:119], v[0:1], v[4:5] op_sel:[0,1,0] op_sel_hi:[1,0,1]
	v_pk_fma_f32 v[6:7], v[114:115], v[20:21], v[6:7]
	v_add_u32_e32 v218, v109, v150
	v_pk_fma_f32 v[18:19], v[116:117], v[0:1], v[18:19]
	v_pk_fma_f32 v[136:137], v[120:121], v[0:1], v[20:21] op_sel:[0,1,0] op_sel_hi:[1,0,1]
	v_pk_fma_f32 v[6:7], v[112:113], v[20:21], v[6:7] op_sel:[0,0,1] op_sel_hi:[1,1,0]
	v_cvt_pk_bf16_f32 v16, v16, v17
	v_add_u32_e32 v219, v218, v142
	v_pk_fma_f32 v[136:137], v[122:123], v[0:1], v[136:137]
	v_pk_fma_f32 v[22:23], v[132:133], v[0:1], v[6:7] op_sel:[0,1,0] op_sel_hi:[1,0,1]
; #define LAS __attribute__((address_space(3)))
; __device__ __forceinline__ unsigned pk2(float lo, float hi) { f32x2 v = {lo, hi}; bf16x2_t b = __builtin_convertvector(v, bf16x2_t); return __builtin_bit_cast(unsigned, b); }
; __device__ __forceinline__ void s5_phase(const bf16_t* __restrict__ HN, bf16_t* __restrict__ Y, const float* __restrict__ rsq, const float* __restrict__ gmix, const float* lam_re, const float* lam_im, const float* log_step, ...
;     ...
;                         for (int grp = 0; grp < 8; ++grp) {
;                             const int r0 = 4 * (grp >> 1);
;                             float c1r, c1i, fr_, fi_, er, ei;
;                             cfma(c1r, c1i, lbr, lbi, zr[r0], zi[r0], zr[r0 + 1], zi[r0 + 1]);
;                             cfma(fr_, fi_, lbr, lbi, c1r, c1i, zr[r0 + 2], zi[r0 + 2]);
;                             cfma(er, ei, lbr, lbi, fr_, fi_, zr[r0 + 3], zi[r0 + 3]);
;                             const float Xr = other_half(xr), Xi = other_half(xi);
;                             float ar, ai, br_, bi_, cr, ci;
;                             cfma(ar, ai, lbr, lbi, Xr, Xi, zr[r0], zi[r0]);
;                             cfma(br_, bi_, l2r, l2i, Xr, Xi, c1r, c1i);
;                             cfma(cr, ci, l3r, l3i, Xr, Xi, fr_, fi_);
;                             cfma(xr, xi, l4r, l4i, Xr, Xi, er, ei);
;                             const bool act = (hi == (grp & 1));
;                             LAS unsigned char* q = xs + (act ? (mb * 32 + 4 * grp) : 64) * S5_XS_ROWB; const int st = act ? S5_XS_ROWB : 0;
;                             *(LAS unsigned*)(q) = pk2(ar, ai); *(LAS unsigned*)(q + st) = pk2(br_, bi_); *(LAS unsigned*)(q + 2 * st) = pk2(cr, ci); *(LAS unsigned*)(q + 3 * st) = pk2(xr, xi);
;                         }
	ds_write_b32 v218, v16
	v_cvt_pk_bf16_f32 v16, v18, v19
	v_add_u32_e32 v220, v218, v144
	v_pk_fma_f32 v[0:1], v[124:125], v[0:1], v[22:23]
	ds_write_b32 v219, v16
	v_cvt_pk_bf16_f32 v16, v136, v137
	v_add_u32_e32 v221, v218, v145
	ds_write_b32 v220, v16
	v_cvt_pk_bf16_f32 v16, v0, v1
	ds_write_b32 v221, v16
	v_mov_b32_e32 v16, v0
	v_mov_b32_e32 v17, v0
	v_mov_b32_e32 v18, v1
	v_mov_b32_e32 v19, v1
	v_permlane32_swap_b32_e32 v16, v17
	s_nop 0
	v_permlane32_swap_b32_e32 v18, v19
	v_xor_b32_e32 v18, v19, v18
	v_xor_b32_e32 v16, v16, v17
	v_xor_b32_e32 v1, v18, v1
	v_xor_b32_e32 v0, v16, v0
	v_pk_fma_f32 v[2:3], v[114:115], v[0:1], v[2:3]
	v_pk_fma_f32 v[4:5], v[118:119], v[0:1], v[4:5] op_sel:[0,1,0] op_sel_hi:[1,0,1]
	v_pk_fma_f32 v[2:3], v[112:113], v[0:1], v[2:3] op_sel:[0,0,1] op_sel_hi:[1,1,0]
	v_add_u32_e32 v222, v109, v151
	v_pk_fma_f32 v[4:5], v[116:117], v[0:1], v[4:5]
	v_pk_fma_f32 v[16:17], v[120:121], v[0:1], v[20:21] op_sel:[0,1,0] op_sel_hi:[1,0,1]
	v_cvt_pk_bf16_f32 v2, v2, v3
	v_add_u32_e32 v223, v222, v146
	v_pk_fma_f32 v[16:17], v[122:123], v[0:1], v[16:17]
	v_pk_fma_f32 v[6:7], v[132:133], v[0:1], v[6:7] op_sel:[0,1,0] op_sel_hi:[1,0,1]
	ds_write_b32 v222, v2
	v_cvt_pk_bf16_f32 v2, v4, v5
	v_add_u32_e32 v224, v222, v148
	v_pk_fma_f32 v[0:1], v[124:125], v[0:1], v[6:7]
	ds_write_b32 v223, v2
	v_cvt_pk_bf16_f32 v2, v16, v17
	v_add_u32_e32 v225, v222, v149
	ds_write_b32 v224, v2
	v_cvt_pk_bf16_f32 v2, v0, v1
	ds_write_b32 v225, v2
	v_mov_b32_e32 v2, v0
	v_mov_b32_e32 v3, v0
	s_nop 1
	v_permlane32_swap_b32_e32 v2, v3
	v_xor_b32_e32 v2, v2, v3
	v_mov_b32_e32 v4, v1
	v_mov_b32_e32 v5, v1
	v_xor_b32_e32 v0, v2, v0
	v_mov_b32_e32 v2, v24
	v_mov_b32_e32 v3, v8
	v_mov_b32_e32 v6, v9
	v_mov_b32_e32 v7, v25
	v_permlane32_swap_b32_e32 v4, v5
	v_pk_fma_f32 v[6:7], v[128:129], v[2:3], v[6:7]
	v_mov_b32_e32 v9, v24
	v_xor_b32_e32 v4, v5, v4
	v_pk_fma_f32 v[6:7], v[112:113], v[8:9], v[6:7]
	v_mov_b32_e32 v16, v26
	v_mov_b32_e32 v17, v10
	v_xor_b32_e32 v1, v4, v1
	v_pk_fma_f32 v[16:17], v[114:115], v[6:7], v[16:17]
	v_pk_fma_f32 v[4:5], v[114:115], v[0:1], v[2:3]
	v_pk_fma_f32 v[16:17], v[112:113], v[6:7], v[16:17] op_sel:[0,0,1] op_sel_hi:[1,1,0]
	v_mov_b32_e32 v10, v27
	v_pk_fma_f32 v[4:5], v[112:113], v[0:1], v[4:5] op_sel:[0,0,1] op_sel_hi:[1,1,0]
	v_pk_fma_f32 v[8:9], v[118:119], v[0:1], v[6:7] op_sel:[0,1,0] op_sel_hi:[1,0,1]
	v_pk_fma_f32 v[10:11], v[114:115], v[16:17], v[10:11]
	v_add_u32_e32 v226, v109, v152
	v_pk_fma_f32 v[8:9], v[116:117], v[0:1], v[8:9]
	v_pk_fma_f32 v[18:19], v[120:121], v[0:1], v[16:17] op_sel:[0,1,0] op_sel_hi:[1,0,1]
	v_pk_fma_f32 v[10:11], v[112:113], v[16:17], v[10:11] op_sel:[0,0,1] op_sel_hi:[1,1,0]
	v_cvt_pk_bf16_f32 v4, v4, v5
	v_add_u32_e32 v227, v226, v142
	v_pk_fma_f32 v[18:19], v[122:123], v[0:1], v[18:19]
	v_pk_fma_f32 v[20:21], v[132:133], v[0:1], v[10:11] op_sel:[0,1,0] op_sel_hi:[1,0,1]
	ds_write_b32 v226, v4
	v_cvt_pk_bf16_f32 v4, v8, v9
	v_add_u32_e32 v228, v226, v144
	v_pk_fma_f32 v[0:1], v[124:125], v[0:1], v[20:21]
	ds_write_b32 v227, v4
	v_cvt_pk_bf16_f32 v4, v18, v19
	v_add_u32_e32 v229, v226, v145
	ds_write_b32 v228, v4
	v_cvt_pk_bf16_f32 v4, v0, v1
	ds_write_b32 v229, v4
	v_mov_b32_e32 v4, v0
	v_mov_b32_e32 v5, v0
	v_mov_b32_e32 v8, v1
	v_mov_b32_e32 v9, v1
	v_permlane32_swap_b32_e32 v4, v5
	s_nop 0
	v_permlane32_swap_b32_e32 v8, v9
	v_xor_b32_e32 v8, v9, v8
	v_xor_b32_e32 v4, v4, v5
	v_xor_b32_e32 v1, v8, v1
	v_xor_b32_e32 v0, v4, v0
	v_pk_fma_f32 v[2:3], v[114:115], v[0:1], v[2:3]
	v_pk_fma_f32 v[4:5], v[118:119], v[0:1], v[6:7] op_sel:[0,1,0] op_sel_hi:[1,0,1]
	v_pk_fma_f32 v[2:3], v[112:113], v[0:1], v[2:3] op_sel:[0,0,1] op_sel_hi:[1,1,0]
	v_add_u32_e32 v230, v109, v153
	v_pk_fma_f32 v[4:5], v[116:117], v[0:1], v[4:5]
	v_pk_fma_f32 v[6:7], v[120:121], v[0:1], v[16:17] op_sel:[0,1,0] op_sel_hi:[1,0,1]
	v_cvt_pk_bf16_f32 v2, v2, v3
	v_add_u32_e32 v231, v230, v146
	v_pk_fma_f32 v[6:7], v[122:123], v[0:1], v[6:7]
	v_pk_fma_f32 v[8:9], v[132:133], v[0:1], v[10:11] op_sel:[0,1,0] op_sel_hi:[1,0,1]
	ds_write_b32 v230, v2
	v_cvt_pk_bf16_f32 v2, v4, v5
	v_add_u32_e32 v232, v230, v148
	v_pk_fma_f32 v[0:1], v[124:125], v[0:1], v[8:9]
	ds_write_b32 v231, v2
	v_cvt_pk_bf16_f32 v2, v6, v7
	v_add_u32_e32 v233, v230, v149
	ds_write_b32 v232, v2
	v_cvt_pk_bf16_f32 v2, v0, v1
	ds_write_b32 v233, v2
	v_mov_b32_e32 v2, v0
	v_mov_b32_e32 v3, v0
	s_nop 1
	v_permlane32_swap_b32_e32 v2, v3
	v_xor_b32_e32 v2, v2, v3
	v_mov_b32_e32 v4, v1
	v_mov_b32_e32 v5, v1
	v_xor_b32_e32 v0, v2, v0
	v_mov_b32_e32 v2, v28
	v_mov_b32_e32 v3, v12
	v_mov_b32_e32 v6, v13
	v_mov_b32_e32 v7, v29
	v_permlane32_swap_b32_e32 v4, v5
	v_pk_fma_f32 v[6:7], v[128:129], v[2:3], v[6:7]
	v_mov_b32_e32 v13, v28
	v_xor_b32_e32 v4, v5, v4
	v_pk_fma_f32 v[6:7], v[112:113], v[12:13], v[6:7]
	v_mov_b32_e32 v10, v30
	v_mov_b32_e32 v11, v14
	v_xor_b32_e32 v1, v4, v1
	v_pk_fma_f32 v[10:11], v[114:115], v[6:7], v[10:11]
	v_pk_fma_f32 v[4:5], v[114:115], v[0:1], v[2:3]
	v_pk_fma_f32 v[10:11], v[112:113], v[6:7], v[10:11] op_sel:[0,0,1] op_sel_hi:[1,1,0]
	v_mov_b32_e32 v14, v31
	v_pk_fma_f32 v[4:5], v[112:113], v[0:1], v[4:5] op_sel:[0,0,1] op_sel_hi:[1,1,0]
	v_pk_fma_f32 v[8:9], v[118:119], v[0:1], v[6:7] op_sel:[0,1,0] op_sel_hi:[1,0,1]
	v_pk_fma_f32 v[14:15], v[114:115], v[10:11], v[14:15]
	v_add_u32_e32 v234, v109, v154
	v_pk_fma_f32 v[8:9], v[116:117], v[0:1], v[8:9]
	v_pk_fma_f32 v[12:13], v[120:121], v[0:1], v[10:11] op_sel:[0,1,0] op_sel_hi:[1,0,1]
	v_pk_fma_f32 v[14:15], v[112:113], v[10:11], v[14:15] op_sel:[0,0,1] op_sel_hi:[1,1,0]
	v_cvt_pk_bf16_f32 v4, v4, v5
	v_add_u32_e32 v235, v234, v142
	v_pk_fma_f32 v[12:13], v[122:123], v[0:1], v[12:13]
; #define LAS __attribute__((address_space(3)))
; __device__ __forceinline__ unsigned pk2(float lo, float hi) { f32x2 v = {lo, hi}; bf16x2_t b = __builtin_convertvector(v, bf16x2_t); return __builtin_bit_cast(unsigned, b); }
; __device__ __forceinline__ void s5_phase(const bf16_t* __restrict__ HN, bf16_t* __restrict__ Y, const float* __restrict__ rsq, const float* __restrict__ gmix, const float* lam_re, const float* lam_im, const float* log_step, ...
;     ...
;                         for (int grp = 0; grp < 8; ++grp) {
;                             const int r0 = 4 * (grp >> 1);
;                             float c1r, c1i, fr_, fi_, er, ei;
;                             cfma(c1r, c1i, lbr, lbi, zr[r0], zi[r0], zr[r0 + 1], zi[r0 + 1]);
;                             cfma(fr_, fi_, lbr, lbi, c1r, c1i, zr[r0 + 2], zi[r0 + 2]);
;                             cfma(er, ei, lbr, lbi, fr_, fi_, zr[r0 + 3], zi[r0 + 3]);
;                             const float Xr = other_half(xr), Xi = other_half(xi);
;                             float ar, ai, br_, bi_, cr, ci;
;                             cfma(ar, ai, lbr, lbi, Xr, Xi, zr[r0], zi[r0]);
;                             cfma(br_, bi_, l2r, l2i, Xr, Xi, c1r, c1i);
;                             cfma(cr, ci, l3r, l3i, Xr, Xi, fr_, fi_);
;                             cfma(xr, xi, l4r, l4i, Xr, Xi, er, ei);
;                             const bool act = (hi == (grp & 1));
;                             LAS unsigned char* q = xs + (act ? (mb * 32 + 4 * grp) : 64) * S5_XS_ROWB; const int st = act ? S5_XS_ROWB : 0;
;                             *(LAS unsigned*)(q) = pk2(ar, ai); *(LAS unsigned*)(q + st) = pk2(br_, bi_); *(LAS unsigned*)(q + 2 * st) = pk2(cr, ci); *(LAS unsigned*)(q + 3 * st) = pk2(xr, xi);
;                         }
	v_pk_fma_f32 v[16:17], v[132:133], v[0:1], v[14:15] op_sel:[0,1,0] op_sel_hi:[1,0,1]
	ds_write_b32 v234, v4
	v_cvt_pk_bf16_f32 v4, v8, v9
	v_add_u32_e32 v236, v234, v144
	v_pk_fma_f32 v[0:1], v[124:125], v[0:1], v[16:17]
	ds_write_b32 v235, v4
	v_cvt_pk_bf16_f32 v4, v12, v13
	v_add_u32_e32 v237, v234, v145
	ds_write_b32 v236, v4
	v_cvt_pk_bf16_f32 v4, v0, v1
	ds_write_b32 v237, v4
	v_mov_b32_e32 v4, v0
	v_mov_b32_e32 v5, v0
	v_mov_b32_e32 v8, v1
	v_mov_b32_e32 v9, v1
	v_permlane32_swap_b32_e32 v4, v5
	s_nop 0
	v_permlane32_swap_b32_e32 v8, v9
	v_xor_b32_e32 v8, v9, v8
	v_xor_b32_e32 v4, v4, v5
	v_xor_b32_e32 v1, v8, v1
	v_xor_b32_e32 v0, v4, v0
	v_pk_fma_f32 v[2:3], v[114:115], v[0:1], v[2:3]
	v_pk_fma_f32 v[4:5], v[118:119], v[0:1], v[6:7] op_sel:[0,1,0] op_sel_hi:[1,0,1]
	v_pk_fma_f32 v[2:3], v[112:113], v[0:1], v[2:3] op_sel:[0,0,1] op_sel_hi:[1,1,0]
	v_pk_fma_f32 v[6:7], v[120:121], v[0:1], v[10:11] op_sel:[0,1,0] op_sel_hi:[1,0,1]
	v_pk_fma_f32 v[8:9], v[132:133], v[0:1], v[14:15] op_sel:[0,1,0] op_sel_hi:[1,0,1]
	v_add_u32_e32 v238, v109, v155
	v_pk_fma_f32 v[4:5], v[116:117], v[0:1], v[4:5]
	v_pk_fma_f32 v[6:7], v[122:123], v[0:1], v[6:7]
	v_pk_fma_f32 v[136:137], v[124:125], v[0:1], v[8:9]
	v_cvt_pk_bf16_f32 v0, v2, v3
	v_add_u32_e32 v239, v238, v146
	ds_write_b32 v238, v0
	v_cvt_pk_bf16_f32 v0, v4, v5
	v_add_u32_e32 v240, v238, v148
	ds_write_b32 v239, v0
	v_cvt_pk_bf16_f32 v0, v6, v7
	v_add_u32_e32 v241, v238, v149
	ds_write_b32 v240, v0
	v_cvt_pk_bf16_f32 v0, v136, v137
	ds_write_b32 v241, v0
	v_mov_b32_e32 v0, v253
	ds_read_b32 v253, v96 offset:256
	v_lshlrev_b32_e32 v2, 16, v56
	v_and_b32_e32 v3, 0xffff0000, v56
	v_mov_b32_e32 v56, v136
	v_add_u32_e32 v195, v109, v156
	v_pk_mul_f32 v[2:3], v[0:1], v[2:3] op_sel_hi:[0,1]
	v_pk_mul_f32 v[2:3], v[36:37], v[2:3]
	v_add_u32_e32 v194, v195, v142
	v_cvt_pk_bf16_f32 v16, v2, v3
	v_lshlrev_b32_e32 v2, 16, v57
	v_and_b32_e32 v3, 0xffff0000, v57
	v_pk_mul_f32 v[2:3], v[0:1], v[2:3] op_sel_hi:[0,1]
	v_pk_mul_f32 v[2:3], v[38:39], v[2:3]
	v_mov_b32_e32 v57, v136
	v_cvt_pk_bf16_f32 v17, v2, v3
	v_lshlrev_b32_e32 v2, 16, v58
	v_and_b32_e32 v3, 0xffff0000, v58
	v_pk_mul_f32 v[2:3], v[0:1], v[2:3] op_sel_hi:[0,1]
	v_pk_mul_f32 v[2:3], v[32:33], v[2:3]
	v_mov_b32_e32 v58, v137
	v_cvt_pk_bf16_f32 v18, v2, v3
	v_lshlrev_b32_e32 v2, 16, v59
	v_and_b32_e32 v3, 0xffff0000, v59
	v_pk_mul_f32 v[0:1], v[0:1], v[2:3] op_sel_hi:[0,1]
	v_pk_mul_f32 v[0:1], v[34:35], v[0:1]
	v_mov_b32_e32 v59, v137
	v_cvt_pk_bf16_f32 v19, v0, v1
	s_nop 0
	v_permlane32_swap_b32_e32 v58, v59
	v_mfma_f32_32x32x16_bf16 v[0:15], v[16:19], v[40:43], 0
	v_permlane32_swap_b32_e32 v56, v57
	v_xor_b32_e32 v58, v59, v58
	v_xor_b32_e32 v56, v57, v56
	v_xor_b32_e32 v57, v58, v137
	v_xor_b32_e32 v56, v56, v136
	v_add_u32_e32 v193, v195, v144
	v_mfma_f32_32x32x16_bf16 v[16:31], v[16:19], v[44:47], 0
	s_nop 4
	v_mov_b32_e32 v59, v0
	v_mov_b32_e32 v196, v1
	v_add_u32_e32 v192, v195, v145
	v_add_u32_e32 v191, v109, v157
	v_add_u32_e32 v190, v191, v146
	v_add_u32_e32 v189, v191, v148
	v_add_u32_e32 v188, v191, v149
	v_mov_b32_e32 v58, v16
	v_mov_b32_e32 v197, v17
	v_pk_fma_f32 v[196:197], v[128:129], v[58:59], v[196:197]
	v_mov_b32_e32 v1, v16
	v_pk_fma_f32 v[0:1], v[112:113], v[0:1], v[196:197]
	v_mov_b32_e32 v196, v18
	v_mov_b32_e32 v197, v2
	v_pk_fma_f32 v[196:197], v[114:115], v[0:1], v[196:197]
	v_mov_b32_e32 v2, v19
	v_pk_fma_f32 v[196:197], v[112:113], v[0:1], v[196:197] op_sel:[0,0,1] op_sel_hi:[1,1,0]
	v_pk_fma_f32 v[136:137], v[114:115], v[56:57], v[58:59]
	v_pk_fma_f32 v[2:3], v[114:115], v[196:197], v[2:3]
	v_pk_fma_f32 v[16:17], v[118:119], v[56:57], v[0:1] op_sel:[0,1,0] op_sel_hi:[1,0,1]
	v_pk_fma_f32 v[2:3], v[112:113], v[196:197], v[2:3] op_sel:[0,0,1] op_sel_hi:[1,1,0]
	v_pk_fma_f32 v[136:137], v[112:113], v[56:57], v[136:137] op_sel:[0,0,1] op_sel_hi:[1,1,0]
	v_pk_fma_f32 v[16:17], v[116:117], v[56:57], v[16:17]
	v_pk_fma_f32 v[198:199], v[120:121], v[56:57], v[196:197] op_sel:[0,1,0] op_sel_hi:[1,0,1]
	v_pk_fma_f32 v[18:19], v[132:133], v[56:57], v[2:3] op_sel:[0,1,0] op_sel_hi:[1,0,1]
	v_pk_fma_f32 v[198:199], v[122:123], v[56:57], v[198:199]
	v_pk_fma_f32 v[18:19], v[124:125], v[56:57], v[18:19]
	v_cvt_pk_bf16_f32 v56, v136, v137
	v_cvt_pk_bf16_f32 v16, v16, v17
	ds_write_b32 v195, v56
	ds_write_b32 v194, v16
	v_cvt_pk_bf16_f32 v16, v198, v199
	ds_write_b32 v193, v16
	v_cvt_pk_bf16_f32 v16, v18, v19
	ds_write_b32 v192, v16
	v_mov_b32_e32 v16, v18
	v_mov_b32_e32 v17, v18
	v_mov_b32_e32 v56, v19
	v_mov_b32_e32 v57, v19
	v_permlane32_swap_b32_e32 v16, v17
	s_nop 0
	v_permlane32_swap_b32_e32 v56, v57
	v_xor_b32_e32 v56, v56, v57
	v_xor_b32_e32 v16, v16, v17
	v_xor_b32_e32 v17, v56, v19
	v_xor_b32_e32 v16, v16, v18
	v_pk_fma_f32 v[18:19], v[114:115], v[16:17], v[58:59]
	v_pk_fma_f32 v[0:1], v[118:119], v[16:17], v[0:1] op_sel:[0,1,0] op_sel_hi:[1,0,1]
	v_pk_fma_f32 v[18:19], v[112:113], v[16:17], v[18:19] op_sel:[0,0,1] op_sel_hi:[1,1,0]
	v_pk_fma_f32 v[0:1], v[116:117], v[16:17], v[0:1]
	v_pk_fma_f32 v[56:57], v[120:121], v[16:17], v[196:197] op_sel:[0,1,0] op_sel_hi:[1,0,1]
	v_pk_fma_f32 v[2:3], v[132:133], v[16:17], v[2:3] op_sel:[0,1,0] op_sel_hi:[1,0,1]
	v_pk_fma_f32 v[56:57], v[122:123], v[16:17], v[56:57]
	v_pk_fma_f32 v[2:3], v[124:125], v[16:17], v[2:3]
	v_cvt_pk_bf16_f32 v16, v18, v19
	v_cvt_pk_bf16_f32 v0, v0, v1
	ds_write_b32 v191, v16
	ds_write_b32 v190, v0
	v_cvt_pk_bf16_f32 v0, v56, v57
	ds_write_b32 v189, v0
	v_cvt_pk_bf16_f32 v0, v2, v3
	ds_write_b32 v188, v0
	v_mov_b32_e32 v0, v2
	v_mov_b32_e32 v1, v2
	v_mov_b32_e32 v16, v3
	v_mov_b32_e32 v17, v3
	v_permlane32_swap_b32_e32 v0, v1
	s_nop 0
; #define LAS __attribute__((address_space(3)))
; __device__ __forceinline__ unsigned pk2(float lo, float hi) { f32x2 v = {lo, hi}; bf16x2_t b = __builtin_convertvector(v, bf16x2_t); return __builtin_bit_cast(unsigned, b); }
; __device__ __forceinline__ void s5_phase(const bf16_t* __restrict__ HN, bf16_t* __restrict__ Y, const float* __restrict__ rsq, const float* __restrict__ gmix, const float* lam_re, const float* lam_im, const float* log_step, ...
;     ...
;                         for (int grp = 0; grp < 8; ++grp) {
;                             const int r0 = 4 * (grp >> 1);
;                             float c1r, c1i, fr_, fi_, er, ei;
;                             cfma(c1r, c1i, lbr, lbi, zr[r0], zi[r0], zr[r0 + 1], zi[r0 + 1]);
;                             cfma(fr_, fi_, lbr, lbi, c1r, c1i, zr[r0 + 2], zi[r0 + 2]);
;                             cfma(er, ei, lbr, lbi, fr_, fi_, zr[r0 + 3], zi[r0 + 3]);
;                             const float Xr = other_half(xr), Xi = other_half(xi);
;                             float ar, ai, br_, bi_, cr, ci;
;                             cfma(ar, ai, lbr, lbi, Xr, Xi, zr[r0], zi[r0]);
;                             cfma(br_, bi_, l2r, l2i, Xr, Xi, c1r, c1i);
;                             cfma(cr, ci, l3r, l3i, Xr, Xi, fr_, fi_);
;                             cfma(xr, xi, l4r, l4i, Xr, Xi, er, ei);
;                             const bool act = (hi == (grp & 1));
;                             LAS unsigned char* q = xs + (act ? (mb * 32 + 4 * grp) : 64) * S5_XS_ROWB; const int st = act ? S5_XS_ROWB : 0;
;                             *(LAS unsigned*)(q) = pk2(ar, ai); *(LAS unsigned*)(q + st) = pk2(br_, bi_); *(LAS unsigned*)(q + 2 * st) = pk2(cr, ci); *(LAS unsigned*)(q + 3 * st) = pk2(xr, xi);
;                         }
	v_permlane32_swap_b32_e32 v16, v17
	v_xor_b32_e32 v16, v16, v17
	v_xor_b32_e32 v0, v0, v1
	v_xor_b32_e32 v1, v16, v3
	v_xor_b32_e32 v0, v0, v2
	v_mov_b32_e32 v2, v20
	v_mov_b32_e32 v3, v4
	v_mov_b32_e32 v18, v5
	v_mov_b32_e32 v19, v21
	v_pk_fma_f32 v[18:19], v[128:129], v[2:3], v[18:19]
	v_mov_b32_e32 v5, v20
	v_pk_fma_f32 v[4:5], v[112:113], v[4:5], v[18:19]
	v_mov_b32_e32 v20, v22
	v_mov_b32_e32 v21, v6
	v_pk_fma_f32 v[20:21], v[114:115], v[4:5], v[20:21]
	v_pk_fma_f32 v[16:17], v[114:115], v[0:1], v[2:3]
	v_pk_fma_f32 v[20:21], v[112:113], v[4:5], v[20:21] op_sel:[0,0,1] op_sel_hi:[1,1,0]
	v_mov_b32_e32 v6, v23
	v_pk_fma_f32 v[16:17], v[112:113], v[0:1], v[16:17] op_sel:[0,0,1] op_sel_hi:[1,1,0]
	v_pk_fma_f32 v[18:19], v[118:119], v[0:1], v[4:5] op_sel:[0,1,0] op_sel_hi:[1,0,1]
	v_pk_fma_f32 v[6:7], v[114:115], v[20:21], v[6:7]
	v_add_u32_e32 v187, v109, v158
	v_pk_fma_f32 v[18:19], v[116:117], v[0:1], v[18:19]
	v_pk_fma_f32 v[56:57], v[120:121], v[0:1], v[20:21] op_sel:[0,1,0] op_sel_hi:[1,0,1]
	v_pk_fma_f32 v[6:7], v[112:113], v[20:21], v[6:7] op_sel:[0,0,1] op_sel_hi:[1,1,0]
	v_cvt_pk_bf16_f32 v16, v16, v17
	v_add_u32_e32 v186, v187, v142
	v_pk_fma_f32 v[56:57], v[122:123], v[0:1], v[56:57]
	v_pk_fma_f32 v[22:23], v[132:133], v[0:1], v[6:7] op_sel:[0,1,0] op_sel_hi:[1,0,1]
	ds_write_b32 v187, v16
	v_cvt_pk_bf16_f32 v16, v18, v19
	v_add_u32_e32 v185, v187, v144
	v_pk_fma_f32 v[0:1], v[124:125], v[0:1], v[22:23]
	ds_write_b32 v186, v16
	v_cvt_pk_bf16_f32 v16, v56, v57
	v_add_u32_e32 v184, v187, v145
	ds_write_b32 v185, v16
	v_cvt_pk_bf16_f32 v16, v0, v1
	ds_write_b32 v184, v16
	v_mov_b32_e32 v16, v0
	v_mov_b32_e32 v17, v0
	v_mov_b32_e32 v18, v1
	v_mov_b32_e32 v19, v1
	v_permlane32_swap_b32_e32 v16, v17
	s_nop 0
	v_permlane32_swap_b32_e32 v18, v19
	v_xor_b32_e32 v18, v19, v18
	v_xor_b32_e32 v16, v16, v17
	v_xor_b32_e32 v1, v18, v1
	v_xor_b32_e32 v0, v16, v0
	v_pk_fma_f32 v[2:3], v[114:115], v[0:1], v[2:3]
	v_pk_fma_f32 v[4:5], v[118:119], v[0:1], v[4:5] op_sel:[0,1,0] op_sel_hi:[1,0,1]
	v_pk_fma_f32 v[2:3], v[112:113], v[0:1], v[2:3] op_sel:[0,0,1] op_sel_hi:[1,1,0]
	v_add_u32_e32 v183, v109, v159
	v_pk_fma_f32 v[4:5], v[116:117], v[0:1], v[4:5]
	v_pk_fma_f32 v[16:17], v[120:121], v[0:1], v[20:21] op_sel:[0,1,0] op_sel_hi:[1,0,1]
	v_cvt_pk_bf16_f32 v2, v2, v3
	v_add_u32_e32 v182, v183, v146
	v_pk_fma_f32 v[16:17], v[122:123], v[0:1], v[16:17]
	v_pk_fma_f32 v[6:7], v[132:133], v[0:1], v[6:7] op_sel:[0,1,0] op_sel_hi:[1,0,1]
	ds_write_b32 v183, v2
	v_cvt_pk_bf16_f32 v2, v4, v5
	v_add_u32_e32 v181, v183, v148
	v_pk_fma_f32 v[0:1], v[124:125], v[0:1], v[6:7]
	ds_write_b32 v182, v2
	v_cvt_pk_bf16_f32 v2, v16, v17
	v_add_u32_e32 v180, v183, v149
	ds_write_b32 v181, v2
	v_cvt_pk_bf16_f32 v2, v0, v1
	ds_write_b32 v180, v2
	v_mov_b32_e32 v2, v0
	v_mov_b32_e32 v3, v0
	s_nop 1
	v_permlane32_swap_b32_e32 v2, v3
	v_xor_b32_e32 v2, v2, v3
	v_mov_b32_e32 v4, v1
	v_mov_b32_e32 v5, v1
	v_xor_b32_e32 v0, v2, v0
	v_mov_b32_e32 v2, v24
	v_mov_b32_e32 v3, v8
	v_mov_b32_e32 v6, v9
	v_mov_b32_e32 v7, v25
	v_permlane32_swap_b32_e32 v4, v5
	v_pk_fma_f32 v[6:7], v[128:129], v[2:3], v[6:7]
	v_mov_b32_e32 v9, v24
	v_xor_b32_e32 v4, v5, v4
	v_pk_fma_f32 v[6:7], v[112:113], v[8:9], v[6:7]
	v_mov_b32_e32 v16, v26
	v_mov_b32_e32 v17, v10
	v_xor_b32_e32 v1, v4, v1
	v_pk_fma_f32 v[16:17], v[114:115], v[6:7], v[16:17]
	v_pk_fma_f32 v[4:5], v[114:115], v[0:1], v[2:3]
	v_pk_fma_f32 v[16:17], v[112:113], v[6:7], v[16:17] op_sel:[0,0,1] op_sel_hi:[1,1,0]
	v_mov_b32_e32 v10, v27
	v_pk_fma_f32 v[4:5], v[112:113], v[0:1], v[4:5] op_sel:[0,0,1] op_sel_hi:[1,1,0]
	v_pk_fma_f32 v[8:9], v[118:119], v[0:1], v[6:7] op_sel:[0,1,0] op_sel_hi:[1,0,1]
	v_pk_fma_f32 v[10:11], v[114:115], v[16:17], v[10:11]
	v_add_u32_e32 v179, v109, v160
	v_pk_fma_f32 v[8:9], v[116:117], v[0:1], v[8:9]
	v_pk_fma_f32 v[18:19], v[120:121], v[0:1], v[16:17] op_sel:[0,1,0] op_sel_hi:[1,0,1]
	v_pk_fma_f32 v[10:11], v[112:113], v[16:17], v[10:11] op_sel:[0,0,1] op_sel_hi:[1,1,0]
	v_cvt_pk_bf16_f32 v4, v4, v5
	v_add_u32_e32 v178, v179, v142
	v_pk_fma_f32 v[18:19], v[122:123], v[0:1], v[18:19]
	v_pk_fma_f32 v[20:21], v[132:133], v[0:1], v[10:11] op_sel:[0,1,0] op_sel_hi:[1,0,1]
	ds_write_b32 v179, v4
	v_cvt_pk_bf16_f32 v4, v8, v9
	v_add_u32_e32 v177, v179, v144
	v_pk_fma_f32 v[0:1], v[124:125], v[0:1], v[20:21]
	ds_write_b32 v178, v4
	v_cvt_pk_bf16_f32 v4, v18, v19
	v_add_u32_e32 v176, v179, v145
	ds_write_b32 v177, v4
	v_cvt_pk_bf16_f32 v4, v0, v1
	ds_write_b32 v176, v4
	v_mov_b32_e32 v4, v0
	v_mov_b32_e32 v5, v0
	v_mov_b32_e32 v8, v1
	v_mov_b32_e32 v9, v1
; #define LAS __attribute__((address_space(3)))
; __device__ __forceinline__ unsigned pk2(float lo, float hi) { f32x2 v = {lo, hi}; bf16x2_t b = __builtin_convertvector(v, bf16x2_t); return __builtin_bit_cast(unsigned, b); }
; #define S5_BAR() asm volatile("s_waitcnt lgkmcnt(0)\n\ts_barrier" ::: "memory")
; __device__ __forceinline__ void s5_phase(const bf16_t* __restrict__ HN, bf16_t* __restrict__ Y, const float* __restrict__ rsq, const float* __restrict__ gmix, const float* lam_re, const float* lam_im, const float* log_step, ...
;     ...
;                         for (int grp = 0; grp < 8; ++grp) {
;                             const int r0 = 4 * (grp >> 1);
;                             float c1r, c1i, fr_, fi_, er, ei;
;                             cfma(c1r, c1i, lbr, lbi, zr[r0], zi[r0], zr[r0 + 1], zi[r0 + 1]);
;                             cfma(fr_, fi_, lbr, lbi, c1r, c1i, zr[r0 + 2], zi[r0 + 2]);
;                             cfma(er, ei, lbr, lbi, fr_, fi_, zr[r0 + 3], zi[r0 + 3]);
;                             const float Xr = other_half(xr), Xi = other_half(xi);
;                             float ar, ai, br_, bi_, cr, ci;
;                             cfma(ar, ai, lbr, lbi, Xr, Xi, zr[r0], zi[r0]);
;                             cfma(br_, bi_, l2r, l2i, Xr, Xi, c1r, c1i);
;                             cfma(cr, ci, l3r, l3i, Xr, Xi, fr_, fi_);
;                             cfma(xr, xi, l4r, l4i, Xr, Xi, er, ei);
;                             const bool act = (hi == (grp & 1));
;                             LAS unsigned char* q = xs + (act ? (mb * 32 + 4 * grp) : 64) * S5_XS_ROWB; const int st = act ? S5_XS_ROWB : 0;
;                             *(LAS unsigned*)(q) = pk2(ar, ai); *(LAS unsigned*)(q + st) = pk2(br_, bi_); *(LAS unsigned*)(q + 2 * st) = pk2(cr, ci); *(LAS unsigned*)(q + 3 * st) = pk2(xr, xi);
;                         }
;                     }
;                     ua[0] = un[0]; ua[1] = un[1];
;                 }
;                 S5_BAR();
	v_permlane32_swap_b32_e32 v4, v5
	s_nop 0
	v_permlane32_swap_b32_e32 v8, v9
	v_xor_b32_e32 v8, v9, v8
	v_xor_b32_e32 v4, v4, v5
	v_xor_b32_e32 v1, v8, v1
	v_xor_b32_e32 v0, v4, v0
	v_pk_fma_f32 v[2:3], v[114:115], v[0:1], v[2:3]
	v_pk_fma_f32 v[4:5], v[118:119], v[0:1], v[6:7] op_sel:[0,1,0] op_sel_hi:[1,0,1]
	v_pk_fma_f32 v[2:3], v[112:113], v[0:1], v[2:3] op_sel:[0,0,1] op_sel_hi:[1,1,0]
	v_add_u32_e32 v175, v109, v161
	v_pk_fma_f32 v[4:5], v[116:117], v[0:1], v[4:5]
	v_pk_fma_f32 v[6:7], v[120:121], v[0:1], v[16:17] op_sel:[0,1,0] op_sel_hi:[1,0,1]
	v_cvt_pk_bf16_f32 v2, v2, v3
	v_add_u32_e32 v174, v175, v146
	v_pk_fma_f32 v[6:7], v[122:123], v[0:1], v[6:7]
	v_pk_fma_f32 v[8:9], v[132:133], v[0:1], v[10:11] op_sel:[0,1,0] op_sel_hi:[1,0,1]
	ds_write_b32 v175, v2
	v_cvt_pk_bf16_f32 v2, v4, v5
	v_add_u32_e32 v173, v175, v148
	v_pk_fma_f32 v[0:1], v[124:125], v[0:1], v[8:9]
	ds_write_b32 v174, v2
	v_cvt_pk_bf16_f32 v2, v6, v7
	v_add_u32_e32 v172, v175, v149
	ds_write_b32 v173, v2
	v_cvt_pk_bf16_f32 v2, v0, v1
	ds_write_b32 v172, v2
	v_mov_b32_e32 v2, v12
	v_mov_b32_e32 v3, v28
	v_mov_b32_e32 v4, v29
	v_mov_b32_e32 v5, v13
	v_mov_b32_e32 v29, v12
	v_mov_b32_e32 v12, v0
	v_mov_b32_e32 v13, v1
	v_pk_fma_f32 v[4:5], v[130:131], v[2:3], v[4:5]
	v_pk_mov_b32 v[10:11], v[0:1], v[0:1] op_sel:[1,0]
	v_permlane32_swap_b32_e32 v0, v12
	v_permlane32_swap_b32_e32 v1, v13
	v_pk_fma_f32 v[4:5], v[112:113], v[28:29], v[4:5]
	v_mov_b32_e32 v6, v30
	v_mov_b32_e32 v7, v14
	v_xor_b32_e32 v0, v0, v12
	v_xor_b32_e32 v12, v13, v1
	v_pk_fma_f32 v[6:7], v[130:131], v[4:5], v[6:7] op_sel:[0,1,0] op_sel_hi:[1,0,1]
	v_xor_b32_e32 v1, v0, v11
	v_xor_b32_e32 v0, v12, v10
	v_pk_fma_f32 v[6:7], v[112:113], v[4:5], v[6:7]
	v_mov_b32_e32 v14, v31
	v_pk_fma_f32 v[10:11], v[128:129], v[0:1], v[2:3]
	v_pk_fma_f32 v[8:9], v[130:131], v[6:7], v[14:15] op_sel:[0,1,0] op_sel_hi:[1,0,1]
	v_pk_fma_f32 v[10:11], v[112:113], v[0:1], v[10:11] op_sel:[0,1,0] op_sel_hi:[1,0,1]
	v_pk_fma_f32 v[12:13], v[118:119], v[0:1], v[4:5] op_sel:[0,0,1] op_sel_hi:[1,1,0]
	v_add_u32_e32 v171, v109, v162
	v_pk_fma_f32 v[8:9], v[112:113], v[6:7], v[8:9]
	v_pk_fma_f32 v[12:13], v[116:117], v[0:1], v[12:13] op_sel:[0,1,0] op_sel_hi:[1,0,1]
	v_pk_fma_f32 v[14:15], v[120:121], v[0:1], v[6:7] op_sel:[0,0,1] op_sel_hi:[1,1,0]
	v_cvt_pk_bf16_f32 v10, v10, v11
	v_add_u32_e32 v170, v171, v142
	v_pk_fma_f32 v[14:15], v[122:123], v[0:1], v[14:15] op_sel:[0,1,0] op_sel_hi:[1,0,1]
	v_pk_fma_f32 v[16:17], v[126:127], v[0:1], v[8:9] op_sel:[0,1,0] op_sel_hi:[1,0,1]
	ds_write_b32 v171, v10
	v_cvt_pk_bf16_f32 v10, v12, v13
	v_add_u32_e32 v169, v171, v144
	v_pk_fma_f32 v[0:1], v[124:125], v[0:1], v[16:17]
	ds_write_b32 v170, v10
	v_cvt_pk_bf16_f32 v10, v14, v15
	ds_write_b32 v169, v10
	v_pk_mov_b32 v[10:11], v[0:1], v[0:1] op_sel:[1,0]
	v_add_u32_e32 v111, v171, v145
	v_cvt_pk_bf16_f32 v10, v10, v11
	ds_write_b32 v111, v10
	v_mov_b32_e32 v10, v1
	v_mov_b32_e32 v11, v1
	v_mov_b32_e32 v12, v0
	v_mov_b32_e32 v13, v0
	v_permlane32_swap_b32_e32 v10, v11
	s_nop 0
	v_permlane32_swap_b32_e32 v12, v13
	v_xor_b32_e32 v10, v10, v11
	v_xor_b32_e32 v11, v13, v12
	v_xor_b32_e32 v1, v10, v1
	v_xor_b32_e32 v0, v11, v0
	v_pk_fma_f32 v[2:3], v[128:129], v[0:1], v[2:3]
	v_pk_fma_f32 v[4:5], v[118:119], v[0:1], v[4:5] op_sel:[0,0,1] op_sel_hi:[1,1,0]
	v_pk_fma_f32 v[2:3], v[112:113], v[0:1], v[2:3] op_sel:[0,1,0] op_sel_hi:[1,0,1]
	v_pk_fma_f32 v[6:7], v[120:121], v[0:1], v[6:7] op_sel:[0,0,1] op_sel_hi:[1,1,0]
	v_pk_fma_f32 v[8:9], v[126:127], v[0:1], v[8:9] op_sel:[0,1,0] op_sel_hi:[1,0,1]
	v_pk_fma_f32 v[4:5], v[116:117], v[0:1], v[4:5] op_sel:[0,1,0] op_sel_hi:[1,0,1]
	v_pk_fma_f32 v[6:7], v[122:123], v[0:1], v[6:7] op_sel:[0,1,0] op_sel_hi:[1,0,1]
	v_pk_fma_f32 v[136:137], v[124:125], v[0:1], v[8:9]
	v_add_u32_e32 v8, v109, v163
	v_cvt_pk_bf16_f32 v0, v2, v3
	ds_write_b32 v8, v0
	v_cvt_pk_bf16_f32 v0, v4, v5
	v_add_u32_e32 v1, v8, v146
	ds_write_b32 v1, v0
	v_cvt_pk_bf16_f32 v0, v6, v7
	v_add_u32_e32 v1, v8, v148
	ds_write_b32 v1, v0
	v_pk_mov_b32 v[0:1], v[136:137], v[136:137] op_sel:[1,0]
	s_add_i32 s2, s2, 1
	v_cvt_pk_bf16_f32 v0, v0, v1
	v_add_u32_e32 v1, v8, v149
	ds_write_b32 v1, v0
	s_waitcnt lgkmcnt(0)
	s_barrier
	s_add_u32 s6, s6, 0x40000
	s_addc_u32 s7, s7, 0
	v_add_u32_e32 v96, 0x100, v96
	s_cmp_eq_u32 s6, 0x800000
	s_waitcnt vmcnt(1)
	v_mov_b32_e32 v0, v48
	v_mov_b32_e32 v1, v49
	v_mov_b32_e32 v2, v50
	v_mov_b32_e32 v3, v51
	s_waitcnt vmcnt(0)
	v_mov_b32_e32 v56, v52
	v_mov_b32_e32 v57, v53
	v_mov_b32_e32 v58, v54
	v_mov_b32_e32 v59, v55
	s_cbranch_scc1 .LBB0_166
